# phase 2 prepares chunks 0..23 only; chunks 24..31 prepared by 128 non-scan workgroups at the start of phase 3 (published with a counter the scan waits on)
# speedup vs baseline: 1.0496x; 1.0034x over previous
; __device__ __forceinline__ void phase_chunk_prep(const Params& p, LAS unsigned char* lds, int wave_s) {
;     ...
;     const int Gd = gridDim.x, per = 2048 / Gd; const bool contig = (per * Gd == 2048);
;     int cur_h = -1;
;     for (int uu = blockIdx.x; uu < 2048; uu += Gd) {
;         const int unit = contig ? (int)blockIdx.x * per + (uu / Gd) : uu;
; __global__ void __launch_bounds__(512, 2) mega(Params p) {
;     ...
;     if (IN(2)) { phase_pool_d(p, wave_s); phase_chunk_prep(p, lds, wave_s); }
.LBB0_641:
	s_cmp_lt_i32 s18, 3
	s_cselect_b64 s[4:5], -1, 0
	s_and_b64 s[26:27], s[4:5], s[0:1]
	s_andn2_b64 vcc, exec, s[26:27]
	s_cbranch_vccnz .LBB0_787
	s_mov_b32 s32, 0
	s_add_i32 s79, s2, 0x600
	s_mov_b64 exec, -1
	s_add_u32 s28, s22, 0xa6aa000
	s_addc_u32 s29, s23, 0
	s_add_u32 s84, s22, 0x64aa000
	s_addc_u32 s85, s23, 0
	v_mbcnt_lo_u32_b32 v0, -1, 0
	v_mbcnt_hi_u32_b32 v0, -1, v0
	v_or_b32_e32 v1, s24, v0
	v_lshl_add_u32 v2, s2, 9, v1
	s_mov_b32 s86, 0

; __device__ __forceinline__ void phase_chunk_prep(const Params& p, LAS unsigned char* lds, int wave_s) {
;     ...
;     const int Gd = gridDim.x, per = 2048 / Gd; const bool contig = (per * Gd == 2048);
;     int cur_h = -1;
;     for (int uu = blockIdx.x; uu < 2048; uu += Gd) {
;         const int unit = contig ? (int)blockIdx.x * per + (uu / Gd) : uu;
;         int tid = tid0; asm volatile("" : "+v"(tid));
;         const int lane = tid & 63, wave = tid >> 6, fr = lane & 15, fq = lane >> 4;
;         const int b = unit >> 9, h = (unit >> 5) & 15, n = unit & 31;
.Lpoold_done:
.LBB0_661:
	s_or_b64 exec, exec, s[30:31]
	s_abs_i32 s3, s33
	v_cvt_f32_u32_e32 v0, s3
	s_mov_b32 s0, 0
	s_mov_b32 s77, -1
	v_mbcnt_lo_u32_b32 v1, -1, s0
	v_rcp_iflag_f32_e32 v0, v0
	v_mbcnt_hi_u32_b32 v1, -1, v1
	v_or_b32_e32 v208, s24, v1
	s_cmpk_gt_i32 s2, 0x7ff
	v_mul_f32_e32 v0, 0x4f7ffffe, v0
	v_cvt_u32_f32_e32 v0, v0
	s_nop 0
	v_readfirstlane_b32 s0, v0
	s_cbranch_scc1 .LBB0_786
	s_sub_i32 s1, 0, s3
	s_mul_i32 s1, s1, s0
	s_mov_b32 s7, 0
	s_mul_hi_u32 s1, s0, s1
	s_add_i32 s8, s0, s1
	s_mov_b32 s9, s7
	s_ashr_i32 s15, s33, 31
	s_lshl_b64 s[0:1], s[8:9], 11
	s_add_u32 s10, s22, 0x63a0000
	s_mul_i32 s0, s1, s3
	s_addc_u32 s11, s23, 0
	s_sub_i32 s0, 0x800, s0
	s_add_i32 s4, s1, 1
	s_sub_i32 s5, s0, s3
	s_cmp_ge_u32 s0, s3
	s_cselect_b32 s1, s4, s1
	s_cselect_b32 s0, s5, s0
	s_add_i32 s4, s1, 1
	s_cmp_ge_u32 s0, s3
	s_cselect_b32 s0, s4, s1
	s_xor_b32 s0, s0, s15
	s_sub_i32 s9, s0, s15
	s_mul_i32 s0, s9, s33
	s_cmpk_eq_i32 s0, 0x800
	s_cselect_b64 s[0:1], -1, 0
	s_add_u32 s25, s22, 0x17d2a000
	s_addc_u32 s38, s23, 0
	s_add_u32 s39, s22, 0x64a8000
	v_cndmask_b32_e64 v0, 0, 1, s[0:1]
	s_mul_i32 s9, s9, s2
	s_addc_u32 s40, s23, 0
	v_cmp_ne_u32_e64 s[0:1], 1, v0
	s_movk_i32 s41, 0x7f
	v_mov_b32_e32 v65, 0
	s_movk_i32 s42, 0x1ff
	s_add_i32 s43, 0, 0x1ca00
	s_movk_i32 s44, 0x1000
	s_movk_i32 s45, 0x2000
	s_movk_i32 s46, 0x3000
	s_movk_i32 s47, 0x4000
	s_add_i32 s48, 0, 0x1d200
	s_movk_i32 s49, 0x3ff
	s_movk_i32 s50, 0x4800
	s_add_i32 s51, 0, 0x1c8fc
	s_movk_i32 s56, 0x110
	s_movk_i32 s57, 0x84
	s_mov_b64 s[12:13], 0x4200
	s_mov_b32 s14, 0x358637bd
	s_mov_b32 s58, 0x800000
	s_movk_i32 s59, 0x4200
	s_add_i32 s60, 0, 0x4400
	s_movk_i32 s61, 0x100
	s_brev_b32 s66, 1
	s_movk_i32 s67, 0xfc00
	s_cmp_eq_u32 s32, 0
	s_cbranch_scc0 .Lcpd_first1
	s_lshr_b32 s4, s2, 2
	s_lshl_b32 s4, s4, 5
	s_and_b32 s5, s2, 3
	s_mul_i32 s5, s5, 6
	s_add_i32 s9, s4, s5
	s_branch .Lcpd_first_done
.Lcpd_first1:
	s_sub_i32 s5, s2, 64
	s_lshr_b32 s4, s5, 1
	s_lshl_b32 s4, s4, 5
	s_and_b32 s5, s5, 1
	s_lshl_b32 s5, s5, 2
	s_add_i32 s9, s4, s5
	s_add_i32 s9, s9, 24
.Lcpd_first_done:
	s_mov_b32 s76, s2
	s_branch .LBB0_664
.LBB0_663:
	s_or_b64 exec, exec, s[4:5]
	s_waitcnt lgkmcnt(0)
	s_barrier
	s_add_i32 s76, s76, s33
	s_cmp_lt_i32 s76, s79
	s_cbranch_scc0 .LBB0_786
.LBB0_664:
	s_and_b64 vcc, exec, s[0:1]
	s_mov_b32 s16, s76
	s_cbranch_vccnz .LBB0_666
	s_sub_i32 s16, s76, s2
	s_lshr_b32 s16, s16, 8
	s_add_i32 s16, s16, s9

; __device__ __forceinline__ void phase_chunk_prep(const Params& p, LAS unsigned char* lds, int wave_s) {
;     ...
;     }
;     __syncthreads();
.LBB0_786:
	s_waitcnt vmcnt(0) lgkmcnt(0)
	s_barrier
	s_cmp_eq_u32 s32, 0
	s_cbranch_scc1 .Lcpd_p2
	s_mov_b32 s32, 0
	s_mov_b64 exec, -1
	v_readlane_b32 s10, v254, 40
	v_readlane_b32 s11, v254, 41
	s_cmp_lg_u32 s24, 0
	s_cbranch_scc1 .Lcpd_back
	v_mbcnt_lo_u32_b32 v0, -1, 0
	v_mbcnt_hi_u32_b32 v0, -1, v0
	v_cmp_eq_u32_e32 vcc, 0, v0
	s_and_saveexec_b64 s[4:5], vcc
	buffer_wbl2 sc1
	s_waitcnt vmcnt(0)
	s_add_u32 s6, s22, 0x1f32d800
	s_addc_u32 s7, s23, 0
	v_mov_b32_e32 v0, 0
	v_mov_b32_e32 v1, 1
	global_atomic_add v0, v1, s[6:7]
	s_waitcnt vmcnt(0)
	s_mov_b64 exec, -1
	s_branch .Lcpd_back
.Lcpd_p2:
.LBB0_787:
	s_cmp_gt_i32 s19, 3
	s_cselect_b64 s[0:1], -1, 0
	s_and_b64 s[4:5], s[26:27], s[0:1]
	s_andn2_b64 vcc, exec, s[4:5]
	s_cbranch_vccnz .LBB0_818
	s_waitcnt vmcnt(0)
	s_waitcnt vmcnt(0)
	s_barrier
	s_mov_b32 s3, 0
	s_nop 0
	v_mbcnt_lo_u32_b32 v0, -1, s3
	v_mbcnt_hi_u32_b32 v0, -1, v0
	v_or_b32_e32 v0, s24, v0
	s_nop 0
	v_cmp_eq_u32_e32 vcc, 0, v0
	s_and_saveexec_b64 s[4:5], vcc
	s_cbranch_execz .LBB0_817
	s_add_i32 s6, 0, 0x23ff0
	v_mov_b32_e32 v0, s6
	s_waitcnt vmcnt(0) expcnt(0) lgkmcnt(0)
	s_getreg_b32 s3, hwreg(HW_REG_XCC_ID, 0, 4)
	ds_read_b32 v1, v0
	s_add_i32 s6, 0, 0x23ff4
	v_mov_b32_e32 v0, s6
	ds_read_b32 v0, v0
	s_and_b32 s3, s3, 15
	s_waitcnt lgkmcnt(1)
	v_cmp_ne_u32_e32 vcc, 0, v1
	s_cbranch_vccnz .LBB0_795
	s_add_u32 s6, s22, 0x1f32a400
	s_addc_u32 s7, s23, 0
	s_add_u32 s8, s22, 0x1f32a500
	s_addc_u32 s9, s23, 0
	s_add_u32 s10, s22, 0x1f32a600
	s_addc_u32 s11, s23, 0
	s_add_u32 s12, s22, 0x1f32a700
	s_addc_u32 s13, s23, 0
	s_add_u32 s14, s22, 0x1f32a800
	s_addc_u32 s15, s23, 0
	s_add_u32 s16, s22, 0x1f32a900
	s_addc_u32 s17, s23, 0
	s_add_u32 s26, s22, 0x1f32aa00
	s_addc_u32 s27, s23, 0
	s_add_u32 s28, s22, 0x1f32ab00
	s_addc_u32 s29, s23, 0
	s_add_u32 s30, s22, 0x1f32ac00
	s_addc_u32 s31, s23, 0
	s_add_u32 s34, s22, 0x1f32ad00
	s_addc_u32 s35, s23, 0
	s_add_u32 s36, s22, 0x1f32ae00
	s_addc_u32 s37, s23, 0
	s_add_u32 s38, s22, 0x1f32af00
	s_addc_u32 s39, s23, 0
	s_add_u32 s40, s22, 0x1f32b000
	s_addc_u32 s41, s23, 0
	s_add_u32 s42, s22, 0x1f32b100
	s_addc_u32 s43, s23, 0
	s_add_u32 s44, s22, 0x1f32b200
	s_addc_u32 s45, s23, 0
	s_add_u32 s46, s22, 0x1f32b300
	s_addc_u32 s47, s23, 0
	v_mov_b32_e32 v16, 0
	s_branch .LBB0_792

; __global__ void __launch_bounds__(512, 2) mega(Params p) {
;     ...
;     if (IN(3)) {
;         if (bx < 64) phase_scan(p, lds, bx, wave_s);
;         else {
;             phase_sample(p, lds, bx - 64, G - 64, wave_s);
;             pg8::Gemm g{(const bf16_t*)(ws + WS_D), (const bf16_t*)(ws + WS_WPOOL), 1024, 256, 256, 33, 4, 256};
;             pg8::StaticOrder S; S.init(33, 4, G - 64, bx - 64);
.LBB0_818:
	s_cmp_lt_i32 s18, 4
	s_cselect_b64 s[4:5], -1, 0
	s_and_b64 s[10:11], s[4:5], s[0:1]
	s_andn2_b64 vcc, exec, s[10:11]
	s_cbranch_vccnz .LBB0_967
	s_cmp_gt_i32 s2, 63
	s_mov_b64 s[0:1], -1
	s_cbranch_scc0 .LBB0_897
	s_cmp_gt_u32 s2, 0xbf
	s_cbranch_scc1 .Lcpd_back
	s_mov_b32 s32, 1
	v_writelane_b32 v254, s10, 40
	v_writelane_b32 v254, s11, 41
	s_add_i32 s79, s2, 0x400
	s_add_u32 s28, s22, 0xa6aa000
	s_addc_u32 s29, s23, 0
	s_mov_b64 s[30:31], 0
	s_mov_b64 exec, -1
	s_branch .LBB0_661
; __device__ __forceinline__ void sample_load(const Params& p, int su, int tid, SamplePre& P) {
;     const int s = su >> 4, h = su & 15, e = tid & 127, dg = tid >> 7; const size_t prow = (size_t)(MP + s);
;     const bf16_t* PROJ = (const bf16_t*)(p.ws + WS_PROJ); const float* GB = (const float*)(p.ws + WS_GB);
;     const float* S0 = p.in[6] + (size_t)su * 16384 + (size_t)(dg * 32) * 128 + e;
; #pragma unroll
;     for (int i = 0; i < 32; ++i) P.sraw[i] = __builtin_nontemporal_load(&S0[i * 128]);
;     { const int ch = tid < 384 ? tid : 0; const int which = ch >> 7, dd = ch & 127, col = which * 2048 + h * 128 + dd;
;       const float* cw = p.in[11] + col; const float* sc = p.in[5] + (size_t)s * 3 * 6144 + col;
;       P.cw[0] = cw[0]; P.cw[1] = cw[6144]; P.cw[2] = cw[2 * 6144]; P.cw[3] = cw[3 * 6144];
;       P.sc[0] = sc[0]; P.sc[1] = sc[6144]; P.sc[2] = sc[2 * 6144]; P.pj = PROJ[prow * NQ + 1024 + col]; }
;     P.g = GB[prow * 32 + h]; P.be = GB[prow * 32 + 16 + h];
;     P.z = PROJ[prow * NQ + 7168 + h * 128 + e];
; }
.Lcpd_back:
	s_mov_b32 s0, 0
	s_sub_i32 s14, s2, 64
	v_mbcnt_lo_u32_b32 v0, -1, s0
	s_sub_i32 s12, s33, 64
	v_mbcnt_hi_u32_b32 v0, -1, v0
	v_or_b32_e32 v6, s24, v0
	s_cmpk_gt_u32 s14, 0x7ff
	s_cbranch_scc1 .LBB0_835
	s_add_u32 s3, s22, 0x85aa000
	v_ashrrev_i32_e32 v1, 2, v6
	s_addc_u32 s25, s23, 0
	s_lshl_b32 s0, s14, 16
	v_and_b32_e32 v8, 0xffffffe0, v1
	s_add_u32 s0, s64, s0
	v_ashrrev_i32_e32 v9, 31, v8
	v_and_b32_e32 v0, 0x7f, v6
	s_addc_u32 s1, s65, 0
	v_lshlrev_b64 v[28:29], 9, v[8:9]
	v_mov_b32_e32 v3, 0
	v_lshlrev_b32_e32 v2, 2, v0
	v_lshl_add_u64 v[10:11], s[0:1], 0, v[28:29]
	v_lshl_add_u64 v[10:11], v[10:11], 0, v[2:3]
	s_movk_i32 s28, 0x1000
	s_movk_i32 s0, 0x180
	v_add_co_u32_e32 v12, vcc, s28, v10
	s_add_u32 s31, s22, 0x63a0000
	v_cmp_gt_i32_e64 s[0:1], s0, v6
	v_addc_co_u32_e32 v13, vcc, 0, v11, vcc
	s_movk_i32 s29, 0x2000
	s_addc_u32 s34, s23, 0
	v_cndmask_b32_e64 v1, 0, v6, s[0:1]
	v_add_co_u32_e32 v14, vcc, s29, v10
	s_add_u32 s35, s22, 0xa6aa000
	v_and_b32_e32 v4, 0x7f, v1
	v_lshlrev_b32_e32 v1, 4, v1
	s_movk_i32 s7, 0xf800
	v_addc_co_u32_e32 v15, vcc, 0, v11, vcc
	s_movk_i32 s30, 0x3000
	s_addc_u32 s36, s23, 0
	s_and_b32 s8, s2, 15
	v_and_or_b32 v1, v1, s7, v4
	global_load_dword v5, v2, s[80:81]
	global_load_dword v81, v[10:11], off nt
	global_load_dword v80, v[10:11], off offset:512 nt
	global_load_dword v79, v[10:11], off offset:1024 nt
	global_load_dword v78, v[10:11], off offset:1536 nt
	global_load_dword v77, v[10:11], off offset:2048 nt
	global_load_dword v76, v[10:11], off offset:2560 nt
	global_load_dword v75, v[10:11], off offset:3072 nt
	global_load_dword v74, v[10:11], off offset:3584 nt
	v_add_co_u32_e32 v10, vcc, s30, v10
	v_lshl_or_b32 v18, s8, 7, v1
	s_nop 0
	v_addc_co_u32_e32 v11, vcc, 0, v11, vcc
	v_ashrrev_i32_e32 v19, 31, v18
	global_load_dword v82, v[14:15], off offset:-4096 nt
	global_load_dword v83, v[14:15], off nt
	global_load_dword v84, v[14:15], off offset:512 nt
	global_load_dword v86, v[14:15], off offset:1024 nt
	global_load_dword v88, v[14:15], off offset:1536 nt
	global_load_dword v89, v[14:15], off offset:2048 nt
	global_load_dword v90, v[14:15], off offset:2560 nt
	global_load_dword v91, v[14:15], off offset:3072 nt
	global_load_dword v92, v[14:15], off offset:3584 nt
	global_load_dword v87, v[12:13], off offset:512 nt
	global_load_dword v85, v[12:13], off offset:1024 nt
	global_load_dword v93, v[12:13], off offset:1536 nt
	global_load_dword v94, v[12:13], off offset:2048 nt
	global_load_dword v95, v[12:13], off offset:2560 nt
	global_load_dword v96, v[12:13], off offset:3072 nt
	global_load_dword v97, v[12:13], off offset:3584 nt
	global_load_dword v98, v[10:11], off nt
	global_load_dword v99, v[10:11], off offset:512 nt
	global_load_dword v100, v[10:11], off offset:1024 nt
	global_load_dword v101, v[10:11], off offset:1536 nt
	global_load_dword v102, v[10:11], off offset:2048 nt
	global_load_dword v103, v[10:11], off offset:2560 nt
	global_load_dword v104, v[10:11], off offset:3072 nt
	global_load_dword v105, v[10:11], off offset:3584 nt
	v_lshlrev_b64 v[10:11], 2, v[18:19]
	s_lshr_b32 s6, s14, 4
	v_lshl_add_u64 v[14:15], s[74:75], 0, v[10:11]
	s_movk_i32 s38, 0x6000
	s_or_b32 s4, s6, 0x2000
	s_mul_i32 s6, s6, 0x12000
	v_add_co_u32_e32 v16, vcc, s38, v14
	s_add_u32 s6, s62, s6
	s_nop 0
	v_addc_co_u32_e32 v17, vcc, 0, v15, vcc
	s_mov_b32 s39, 0xc000
	s_addc_u32 s7, s63, 0
	v_add_co_u32_e32 v20, vcc, s39, v14
	s_mov_b32 s37, 0x12000
	v_lshl_add_u64 v[10:11], s[6:7], 0, v[10:11]
	v_addc_co_u32_e32 v21, vcc, 0, v15, vcc
	s_mul_i32 s6, s4, 0x4800
	s_mov_b32 s5, 0
	v_add_co_u32_e32 v22, vcc, s37, v14
	s_mul_hi_u32 s7, s4, 0x4800
	s_add_u32 s6, s35, s6
	v_addc_co_u32_e32 v23, vcc, 0, v15, vcc
	s_addc_u32 s7, s36, s7
	s_lshl_b64 s[4:5], s[4:5], 7
	global_load_dword v12, v[14:15], off
	global_load_dword v13, v[16:17], off
	s_nop 0
	global_load_dword v14, v[20:21], off
	global_load_dword v15, v[22:23], off
	global_load_dword v16, v[10:11], off
	v_add_co_u32_e32 v20, vcc, s38, v10
	s_add_u32 s4, s31, s4
	s_nop 0
	v_addc_co_u32_e32 v21, vcc, 0, v11, vcc
	s_addc_u32 s5, s34, s5
	s_lshl_b32 s9, s8, 2
	s_lshl_b32 s8, s8, 8
	v_add_co_u32_e32 v10, vcc, s39, v10
	v_lshl_add_u64 v[18:19], v[18:19], 1, s[6:7]
	s_add_u32 s6, s6, s8
	v_addc_co_u32_e32 v11, vcc, 0, v11, vcc
	global_load_dword v17, v[20:21], off
	s_nop 0
	global_load_dword v10, v[10:11], off
	s_addc_u32 s7, s7, 0
	v_lshlrev_b32_e32 v20, 1, v0
	v_mov_b32_e32 v21, v3
	v_lshl_add_u64 v[20:21], s[6:7], 0, v[20:21]
	v_mov_b32_e32 v4, s9
	v_add_co_u32_e32 v20, vcc, s30, v20
	s_lshl_b32 s8, s2, 7
	s_nop 0
	v_addc_co_u32_e32 v21, vcc, 0, v21, vcc
	global_load_ushort v11, v[18:19], off offset:2048
	global_load_dword v106, v4, s[4:5]
	global_load_dword v73, v4, s[4:5] offset:64
	s_nop 0
	global_load_ushort v4, v[20:21], off offset:2048
	v_mbcnt_lo_u32_b32 v19, -1, 0
	v_mbcnt_hi_u32_b32 v24, -1, v19
	v_and_b32_e32 v19, 64, v24
	v_add_u32_e32 v25, 64, v19
	v_xor_b32_e32 v19, 1, v24
	v_cmp_lt_i32_e32 vcc, v19, v25
	v_xor_b32_e32 v20, 2, v24
	v_xor_b32_e32 v21, 4, v24
	v_cndmask_b32_e32 v19, v24, v19, vcc
	v_cmp_lt_i32_e32 vcc, v20, v25
	v_xor_b32_e32 v22, 8, v24
	s_ashr_i32 s15, s14, 31
	v_cndmask_b32_e32 v20, v24, v20, vcc
	v_cmp_lt_i32_e32 vcc, v21, v25
	v_and_b32_e32 v9, 63, v6
	v_xor_b32_e32 v23, 16, v24
	v_cndmask_b32_e32 v21, v24, v21, vcc
	v_cmp_lt_i32_e32 vcc, v22, v25
	s_add_i32 s40, s8, 0xffffe000
	s_lshl_b64 s[8:9], s[14:15], 16
	v_cndmask_b32_e32 v22, v24, v22, vcc
	v_cmp_lt_i32_e32 vcc, v23, v25
	v_xor_b32_e32 v26, 32, v24
	v_cmp_eq_u32_e64 s[4:5], 0, v9
	v_lshl_add_u32 v27, v8, 2, 0
	v_lshl_add_u64 v[8:9], s[8:9], 0, v[28:29]
	v_ashrrev_i32_e32 v7, 6, v6
	v_cndmask_b32_e32 v23, v24, v23, vcc
	v_cmp_lt_i32_e32 vcc, v26, v25
	s_movk_i32 s6, 0x80
	v_or_b32_e32 v8, v8, v2
	v_lshl_add_u32 v18, v6, 2, 0
	v_cndmask_b32_e32 v24, v24, v26, vcc
	v_lshl_add_u32 v25, v7, 2, 0
	v_and_b32_e32 v30, 0xffffff80, v6
	v_cmp_gt_i32_e64 s[6:7], s6, v6
	v_lshl_add_u64 v[6:7], s[64:65], 0, v[28:29]
	s_lshl_b32 s41, s33, 7
	v_lshl_add_u64 v[8:9], s[20:21], 0, v[8:9]
	s_mov_b64 s[8:9], 0x5604000
	s_ashr_i32 s13, s12, 31
	v_lshlrev_b32_e32 v19, 2, v19
	v_lshlrev_b32_e32 v20, 2, v20
	v_lshlrev_b32_e32 v21, 2, v21
	v_lshlrev_b32_e32 v22, 2, v22
	v_lshlrev_b32_e32 v23, 2, v23
	v_lshlrev_b32_e32 v24, 2, v24
	v_add_u32_e32 v26, 0, v2
	v_lshl_add_u64 v[6:7], v[6:7], 0, v[2:3]
	s_addk_i32 s41, 0xe000
	v_lshl_add_u64 v[8:9], v[8:9], 0, s[8:9]
	s_lshl_b64 s[16:17], s[12:13], 16
	s_mov_b32 s13, 0x800000
	v_add_u32_e32 v28, 0, v30
	v_mov_b32_e32 v29, 0x358637bd
	s_mov_b32 s15, s14
	s_branch .LBB0_823

; #define LAS __attribute__((address_space(3)))
; #define SCAN_COPY(srcbase, bufidx) do { _Pragma("unroll") for (int k = 0; k < 8; ++k) { const int pc = wave + 8 * k; if (pc < IMG_PIECES) \
;         __builtin_amdgcn_global_load_lds((const unsigned*)((srcbase) + pc * 1024 + lane * 16), (LAS unsigned*)(lds + (bufidx) * IMG_BYTES + pc * 1024), 16, 0, 0); } } while (0)
; #define SCAN_LOAD(n_, uu, z0, z1, gl) do { const float* U_ = U0 + (size_t)(n_) * 8192; const bf16_t* Z_ = Z0 + (size_t)(n_) * 64 * NQ; \
;         z0 = *(const u32x4*)Z_; z1 = *(const u32x4*)(Z_ + 8); \
;         _Pragma("unroll") for (int mm = 0; mm < 4; ++mm) uu[mm] = *(const f32x4*)(U_ + mm * 256); \
;         gl = GL[unit0 + (n_)]; } while (0)
; __device__ __forceinline__ void phase_scan(const Params& p, LAS unsigned char* lds, int bh, int wave_s) {
;     ...
;     for (int n = 0; n < 32; ++n) {
;         const int cur = n & 1;
;         const LAS bf16_t* img = (const LAS bf16_t*)(lds + cur * IMG_BYTES);
;         const bool hasn = (n + 1 < 32);
;         f32x4 unext[4]; float glnext = 0.f;
;         { const int np = hasn ? n + 1 : n;
;           SCAN_COPY(chunk0 + (size_t)np * IMG_BYTES, cur ^ 1); SCAN_LOAD(np, unext, zr0, zr1, glnext); }
.LBB0_918:
	s_cmp_eq_u32 s3, 24
	s_cbranch_scc0 .Lscanw_skip
	s_add_u32 s84, s22, 0x1f32d800
	s_addc_u32 s85, s23, 0
	v_mov_b32_e32 v48, 0
	s_mov_b32 s86, 0
.Lscanw_loop:
	global_load_dword v49, v48, s[84:85] sc1
	s_waitcnt vmcnt(0)
	v_readfirstlane_b32 s87, v49
	s_nop 3
	s_cmp_ge_u32 s87, 0x80
	s_cbranch_scc1 .Lscanw_done
	s_sleep 8
	s_add_i32 s86, s86, 1
	s_cmp_lt_u32 s86, 0x40000
	s_cbranch_scc1 .Lscanw_loop
.Lscanw_done:
	buffer_inv sc1
.Lscanw_skip:
	s_add_i32 s36, s3, -1
	s_and_b32 s57, s36, 1
	s_cmp_lg_u32 s50, 0x7c0000
	s_cselect_b32 s56, s3, 31
	s_mul_i32 s36, s56, 0xec00
	v_lshl_add_u64 v[48:49], v[74:75], 0, s[36:37]
	s_xor_b32 s36, s57, 1
	s_mul_i32 s36, s36, 0xec00
	s_add_i32 s36, s36, 0
	v_lshl_add_u64 v[200:201], v[48:49], 0, s[4:5]
	s_add_i32 s84, s36, s4
	v_lshl_add_u64 v[202:203], v[48:49], 0, s[38:39]
	s_add_i32 s85, s36, s38
	v_lshl_add_u64 v[204:205], v[48:49], 0, s[40:41]
	s_add_i32 s86, s36, s40
	v_lshl_add_u64 v[206:207], v[48:49], 0, s[42:43]
	s_add_i32 s87, s36, s42
	v_lshl_add_u64 v[208:209], v[48:49], 0, s[44:45]
	s_add_i32 s88, s36, s44
	v_lshl_add_u64 v[210:211], v[48:49], 0, s[46:47]
	s_add_i32 s89, s36, s46
	v_lshl_add_u64 v[212:213], v[48:49], 0, s[48:49]
	s_add_i32 s90, s36, s48
	v_lshl_add_u64 v[214:215], v[48:49], 0, s[34:35]
	s_add_i32 s91, s36, s34
	s_mov_b32 m0, s84
	s_nop 0
	global_load_lds_dwordx4 v[200:201], off
	s_mov_b32 m0, s85
	s_nop 0
	global_load_lds_dwordx4 v[202:203], off
